# mLSTM scan items remapped: 512 full word-groups in round one, the 64 32-word remainders in round two (work balance)
# speedup vs baseline: 1.0087x; 1.0087x over previous
; DI unsigned pk_bf16(float a, float b) { f32x2 v = {a, b}; bf16v2 r = __builtin_convertvector(v, bf16v2); return __builtin_bit_cast(unsigned, r); }
; DI float bflo(unsigned w) { return __uint_as_float(w << 16); }
; DI float bfhi(unsigned w) { return __uint_as_float(w & 0xffff0000u); }
; DI int otid() { int t = threadIdx.x & 255; asm volatile("" : "+v"(t)); return t; }
; DI void scan_item(const Params& p, int item) {
;     const int chain = item / 9, wd = (item % 9) * THREADS + otid();
;     if (wd >= STSZ / 2) return;
;     unsigned* st = (unsigned*)(p.ST + (size_t)chain * NCH * STSZ) + wd;
;     const float* dec = p.DEC + chain * NCH;
;     float S0 = 0.f, S1 = 0.f;
;     for (int q0 = 0; q0 < NCH; q0 += 22) {
;         unsigned tmp[22]; float dd[22];
; #pragma unroll
;         for (int i = 0; i < 22; ++i) { tmp[i] = st[(size_t)(q0 + i) * (STSZ / 2)]; dd[i] = dec[q0 + i]; }
; #pragma unroll
;         for (int i = 0; i < 22; ++i) { st[(size_t)(q0 + i) * (STSZ / 2)] = pk_bf16(S0, S1); S0 = dd[i] * S0 + bflo(tmp[i]); S1 = dd[i] * S1 + bfhi(tmp[i]); }
;     }
; DI void run_phase(int ph, char* smem) {
;     ...
;         for (int it = bid; it < 64 * 9; it += G) scan_item(p, it);
.LBB0_133:
	s_lshr_b32 s12, s10, 3
	s_add_i32 s12, s12, s10
	s_add_i32 s13, s10, 0xfffffe00
	s_mul_i32 s13, s13, 9
	s_add_i32 s13, s13, 8
	s_cmpk_lt_i32 s10, 0x200
	s_cselect_b32 s12, s12, s13
	s_mul_hi_i32 s0, s12, 0x38e38e39
	s_lshr_b32 s1, s0, 31
	s_ashr_i32 s4, s0, 1
	s_add_i32 s4, s4, s1
	s_mul_i32 s0, s4, 9
	v_mov_b32_e32 v0, v228
	s_sub_i32 s0, s12, s0
	s_nop 0
	v_lshl_add_u32 v0, s0, 8, v0
	s_movk_i32 s0, 0x820
	v_cmp_gt_i32_e32 vcc, s0, v0
	s_and_saveexec_b64 s[0:1], vcc
	s_movk_i32 s15, 0x2000
	s_cbranch_execz .LBB0_132
	s_mul_hi_i32 s11, s4, 0x10c200
	s_mul_i32 s12, s4, 0x10c200
	s_mulk_i32 s4, 0x84
	s_ashr_i32 s5, s4, 31
	s_add_u32 s12, s6, s12
	s_addc_u32 s13, s7, s11
	s_lshl_b64 s[4:5], s[4:5], 2
	v_ashrrev_i32_e32 v1, 31, v0
	s_add_u32 s4, s8, s4
	v_mov_b32_e32 v19, 0
	v_lshl_add_u64 v[16:17], v[0:1], 2, s[12:13]
	s_addc_u32 s5, s9, s5
	s_movk_i32 s11, 0xffea
	v_mov_b32_e32 v18, v19
